# P7 K-split reduce: 16 slab loads kept in flight continuously instead of 12 drained batches of 8 (same addition order)
# baseline (speedup 1.0000x reference)
.Lks7_wait_done:
	s_or_b64 exec, exec, s[96:97]
	s_barrier
	s_lshl_b32 s86, s88, 18
	s_add_u32 s92, s92, s86
	s_addc_u32 s93, s93, 0
	global_load_dwordx4 v[128:131], v244, s[92:93]
	s_add_u32 s92, s92, 0x2000
	s_addc_u32 s93, s93, 0
	global_load_dwordx4 v[132:135], v244, s[92:93]
	s_add_u32 s92, s92, 0x2000
	s_addc_u32 s93, s93, 0
	global_load_dwordx4 v[136:139], v244, s[92:93]
	s_add_u32 s92, s92, 0x2000
	s_addc_u32 s93, s93, 0
	global_load_dwordx4 v[140:143], v244, s[92:93]
	s_add_u32 s92, s92, 0x2000
	s_addc_u32 s93, s93, 0
	global_load_dwordx4 v[144:147], v244, s[92:93]
	s_add_u32 s92, s92, 0x2000
	s_addc_u32 s93, s93, 0
	global_load_dwordx4 v[148:151], v244, s[92:93]
	s_add_u32 s92, s92, 0x2000
	s_addc_u32 s93, s93, 0
	global_load_dwordx4 v[152:155], v244, s[92:93]
	s_add_u32 s92, s92, 0x2000
	s_addc_u32 s93, s93, 0
	global_load_dwordx4 v[156:159], v244, s[92:93]
	s_add_u32 s92, s92, 0x2000
	s_addc_u32 s93, s93, 0
	global_load_dwordx4 v[164:167], v244, s[92:93]
	s_add_u32 s92, s92, 0x2000
	s_addc_u32 s93, s93, 0
	global_load_dwordx4 v[168:171], v244, s[92:93]
	s_add_u32 s92, s92, 0x2000
	s_addc_u32 s93, s93, 0
	global_load_dwordx4 v[172:175], v244, s[92:93]
	s_add_u32 s92, s92, 0x2000
	s_addc_u32 s93, s93, 0
	global_load_dwordx4 v[176:179], v244, s[92:93]
	s_add_u32 s92, s92, 0x2000
	s_addc_u32 s93, s93, 0
	global_load_dwordx4 v[180:183], v244, s[92:93]
	s_add_u32 s92, s92, 0x2000
	s_addc_u32 s93, s93, 0
	global_load_dwordx4 v[184:187], v244, s[92:93]
	s_add_u32 s92, s92, 0x2000
	s_addc_u32 s93, s93, 0
	global_load_dwordx4 v[188:191], v244, s[92:93]
	s_add_u32 s92, s92, 0x2000
	s_addc_u32 s93, s93, 0
	global_load_dwordx4 v[208:211], v244, s[92:93]
	s_add_u32 s92, s92, 0x2000
	s_addc_u32 s93, s93, 0
	s_waitcnt vmcnt(15)
	v_add_f32_e32 v0, v0, v128
	v_add_f32_e32 v1, v1, v129
	v_add_f32_e32 v2, v2, v130
	v_add_f32_e32 v3, v3, v131
	global_load_dwordx4 v[128:131], v244, s[92:93]
	s_add_u32 s92, s92, 0x2000
	s_addc_u32 s93, s93, 0
	s_waitcnt vmcnt(15)
	v_add_f32_e32 v4, v4, v132
	v_add_f32_e32 v5, v5, v133
	v_add_f32_e32 v6, v6, v134
	v_add_f32_e32 v7, v7, v135
	global_load_dwordx4 v[132:135], v244, s[92:93]
	s_add_u32 s92, s92, 0x2000
	s_addc_u32 s93, s93, 0
	s_waitcnt vmcnt(15)
	v_add_f32_e32 v8, v8, v136
	v_add_f32_e32 v9, v9, v137
	v_add_f32_e32 v10, v10, v138
	v_add_f32_e32 v11, v11, v139
	global_load_dwordx4 v[136:139], v244, s[92:93]
	s_add_u32 s92, s92, 0x2000
	s_addc_u32 s93, s93, 0
	s_waitcnt vmcnt(15)
	v_add_f32_e32 v12, v12, v140
	v_add_f32_e32 v13, v13, v141
	v_add_f32_e32 v14, v14, v142
	v_add_f32_e32 v15, v15, v143
	global_load_dwordx4 v[140:143], v244, s[92:93]
	s_add_u32 s92, s92, 0x2000
	s_addc_u32 s93, s93, 0
	s_waitcnt vmcnt(15)
	v_add_f32_e32 v16, v16, v144
	v_add_f32_e32 v17, v17, v145
	v_add_f32_e32 v18, v18, v146
	v_add_f32_e32 v19, v19, v147
	global_load_dwordx4 v[144:147], v244, s[92:93]
	s_add_u32 s92, s92, 0x2000
	s_addc_u32 s93, s93, 0
	s_waitcnt vmcnt(15)
	v_add_f32_e32 v20, v20, v148
	v_add_f32_e32 v21, v21, v149
	v_add_f32_e32 v22, v22, v150
	v_add_f32_e32 v23, v23, v151
	global_load_dwordx4 v[148:151], v244, s[92:93]
	s_add_u32 s92, s92, 0x2000
	s_addc_u32 s93, s93, 0
	s_waitcnt vmcnt(15)
	v_add_f32_e32 v24, v24, v152
	v_add_f32_e32 v25, v25, v153
	v_add_f32_e32 v26, v26, v154
	v_add_f32_e32 v27, v27, v155
	global_load_dwordx4 v[152:155], v244, s[92:93]
	s_add_u32 s92, s92, 0x2000
	s_addc_u32 s93, s93, 0
	s_waitcnt vmcnt(15)
	v_add_f32_e32 v28, v28, v156
	v_add_f32_e32 v29, v29, v157
	v_add_f32_e32 v30, v30, v158
	v_add_f32_e32 v31, v31, v159
	global_load_dwordx4 v[156:159], v244, s[92:93]
	s_add_u32 s92, s92, 0x2000
	s_addc_u32 s93, s93, 0
	s_waitcnt vmcnt(15)
	v_add_f32_e32 v32, v32, v164
	v_add_f32_e32 v33, v33, v165
	v_add_f32_e32 v34, v34, v166
	v_add_f32_e32 v35, v35, v167
	global_load_dwordx4 v[164:167], v244, s[92:93]
	s_add_u32 s92, s92, 0x2000
	s_addc_u32 s93, s93, 0
	s_waitcnt vmcnt(15)
	v_add_f32_e32 v36, v36, v168
	v_add_f32_e32 v37, v37, v169
	v_add_f32_e32 v38, v38, v170
	v_add_f32_e32 v39, v39, v171
	global_load_dwordx4 v[168:171], v244, s[92:93]
	s_add_u32 s92, s92, 0x2000
	s_addc_u32 s93, s93, 0
	s_waitcnt vmcnt(15)
	v_add_f32_e32 v40, v40, v172
	v_add_f32_e32 v41, v41, v173
	v_add_f32_e32 v42, v42, v174
	v_add_f32_e32 v43, v43, v175
	global_load_dwordx4 v[172:175], v244, s[92:93]
	s_add_u32 s92, s92, 0x2000
	s_addc_u32 s93, s93, 0
	s_waitcnt vmcnt(15)
	v_add_f32_e32 v44, v44, v176
	v_add_f32_e32 v45, v45, v177
	v_add_f32_e32 v46, v46, v178
	v_add_f32_e32 v47, v47, v179
	global_load_dwordx4 v[176:179], v244, s[92:93]
	s_add_u32 s92, s92, 0x2000
	s_addc_u32 s93, s93, 0
	s_waitcnt vmcnt(15)
	v_add_f32_e32 v48, v48, v180
	v_add_f32_e32 v49, v49, v181
	v_add_f32_e32 v50, v50, v182
	v_add_f32_e32 v51, v51, v183
	global_load_dwordx4 v[180:183], v244, s[92:93]
	s_add_u32 s92, s92, 0x2000
	s_addc_u32 s93, s93, 0
	s_waitcnt vmcnt(15)
	v_add_f32_e32 v52, v52, v184
	v_add_f32_e32 v53, v53, v185
	v_add_f32_e32 v54, v54, v186
	v_add_f32_e32 v55, v55, v187
	global_load_dwordx4 v[184:187], v244, s[92:93]
	s_add_u32 s92, s92, 0x2000
	s_addc_u32 s93, s93, 0
	s_waitcnt vmcnt(15)
	v_add_f32_e32 v56, v56, v188
	v_add_f32_e32 v57, v57, v189
	v_add_f32_e32 v58, v58, v190
	v_add_f32_e32 v59, v59, v191
	global_load_dwordx4 v[188:191], v244, s[92:93]
	s_add_u32 s92, s92, 0x2000
	s_addc_u32 s93, s93, 0
	s_waitcnt vmcnt(15)
	v_add_f32_e32 v60, v60, v208
	v_add_f32_e32 v61, v61, v209
	v_add_f32_e32 v62, v62, v210
	v_add_f32_e32 v63, v63, v211
	global_load_dwordx4 v[208:211], v244, s[92:93]
	s_add_u32 s92, s92, 0x2000
	s_addc_u32 s93, s93, 0
	s_add_u32 s92, s92, 0xc0000
	s_addc_u32 s93, s93, 0
	s_waitcnt vmcnt(15)
	v_add_f32_e32 v64, v64, v128
	v_add_f32_e32 v65, v65, v129
	v_add_f32_e32 v66, v66, v130
	v_add_f32_e32 v67, v67, v131
	global_load_dwordx4 v[128:131], v244, s[92:93]
	s_add_u32 s92, s92, 0x2000
	s_addc_u32 s93, s93, 0
	s_waitcnt vmcnt(15)
	v_add_f32_e32 v68, v68, v132
	v_add_f32_e32 v69, v69, v133
	v_add_f32_e32 v70, v70, v134
	v_add_f32_e32 v71, v71, v135
	global_load_dwordx4 v[132:135], v244, s[92:93]
	s_add_u32 s92, s92, 0x2000
	s_addc_u32 s93, s93, 0
	s_waitcnt vmcnt(15)
	v_add_f32_e32 v72, v72, v136
	v_add_f32_e32 v73, v73, v137
	v_add_f32_e32 v74, v74, v138
	v_add_f32_e32 v75, v75, v139
	global_load_dwordx4 v[136:139], v244, s[92:93]
	s_add_u32 s92, s92, 0x2000
	s_addc_u32 s93, s93, 0
	s_waitcnt vmcnt(15)
	v_add_f32_e32 v76, v76, v140
	v_add_f32_e32 v77, v77, v141
	v_add_f32_e32 v78, v78, v142
	v_add_f32_e32 v79, v79, v143
	global_load_dwordx4 v[140:143], v244, s[92:93]
	s_add_u32 s92, s92, 0x2000
	s_addc_u32 s93, s93, 0
	s_waitcnt vmcnt(15)
	v_add_f32_e32 v80, v80, v144
	v_add_f32_e32 v81, v81, v145
	v_add_f32_e32 v82, v82, v146
	v_add_f32_e32 v83, v83, v147
	global_load_dwordx4 v[144:147], v244, s[92:93]
	s_add_u32 s92, s92, 0x2000
	s_addc_u32 s93, s93, 0
	s_waitcnt vmcnt(15)
	v_add_f32_e32 v84, v84, v148
	v_add_f32_e32 v85, v85, v149
	v_add_f32_e32 v86, v86, v150
	v_add_f32_e32 v87, v87, v151
	global_load_dwordx4 v[148:151], v244, s[92:93]
	s_add_u32 s92, s92, 0x2000
	s_addc_u32 s93, s93, 0
	s_waitcnt vmcnt(15)
	v_add_f32_e32 v88, v88, v152
	v_add_f32_e32 v89, v89, v153
	v_add_f32_e32 v90, v90, v154
	v_add_f32_e32 v91, v91, v155
	global_load_dwordx4 v[152:155], v244, s[92:93]
	s_add_u32 s92, s92, 0x2000
	s_addc_u32 s93, s93, 0
	s_waitcnt vmcnt(15)
	v_add_f32_e32 v92, v92, v156
	v_add_f32_e32 v93, v93, v157
	v_add_f32_e32 v94, v94, v158
	v_add_f32_e32 v95, v95, v159
	global_load_dwordx4 v[156:159], v244, s[92:93]
	s_add_u32 s92, s92, 0x2000
	s_addc_u32 s93, s93, 0
	s_waitcnt vmcnt(15)
	v_add_f32_e32 v96, v96, v164
	v_add_f32_e32 v97, v97, v165
	v_add_f32_e32 v98, v98, v166
	v_add_f32_e32 v99, v99, v167
	global_load_dwordx4 v[164:167], v244, s[92:93]
	s_add_u32 s92, s92, 0x2000
	s_addc_u32 s93, s93, 0
	s_waitcnt vmcnt(15)
	v_add_f32_e32 v100, v100, v168
	v_add_f32_e32 v101, v101, v169
	v_add_f32_e32 v102, v102, v170
	v_add_f32_e32 v103, v103, v171
	global_load_dwordx4 v[168:171], v244, s[92:93]
	s_add_u32 s92, s92, 0x2000
	s_addc_u32 s93, s93, 0
	s_waitcnt vmcnt(15)
	v_add_f32_e32 v104, v104, v172
	v_add_f32_e32 v105, v105, v173
	v_add_f32_e32 v106, v106, v174
	v_add_f32_e32 v107, v107, v175
	global_load_dwordx4 v[172:175], v244, s[92:93]
	s_add_u32 s92, s92, 0x2000
	s_addc_u32 s93, s93, 0
	s_waitcnt vmcnt(15)
	v_add_f32_e32 v108, v108, v176
	v_add_f32_e32 v109, v109, v177
	v_add_f32_e32 v110, v110, v178
	v_add_f32_e32 v111, v111, v179
	global_load_dwordx4 v[176:179], v244, s[92:93]
	s_add_u32 s92, s92, 0x2000
	s_addc_u32 s93, s93, 0
	s_waitcnt vmcnt(15)
	v_add_f32_e32 v112, v112, v180
	v_add_f32_e32 v113, v113, v181
	v_add_f32_e32 v114, v114, v182
	v_add_f32_e32 v115, v115, v183
	global_load_dwordx4 v[180:183], v244, s[92:93]
	s_add_u32 s92, s92, 0x2000
	s_addc_u32 s93, s93, 0
	s_waitcnt vmcnt(15)
	v_add_f32_e32 v116, v116, v184
	v_add_f32_e32 v117, v117, v185
	v_add_f32_e32 v118, v118, v186
	v_add_f32_e32 v119, v119, v187
	global_load_dwordx4 v[184:187], v244, s[92:93]
	s_add_u32 s92, s92, 0x2000
	s_addc_u32 s93, s93, 0
	s_waitcnt vmcnt(15)
	v_add_f32_e32 v120, v120, v188
	v_add_f32_e32 v121, v121, v189
	v_add_f32_e32 v122, v122, v190
	v_add_f32_e32 v123, v123, v191
	global_load_dwordx4 v[188:191], v244, s[92:93]
	s_add_u32 s92, s92, 0x2000
	s_addc_u32 s93, s93, 0
	s_waitcnt vmcnt(15)
	v_add_f32_e32 v124, v124, v208
	v_add_f32_e32 v125, v125, v209
	v_add_f32_e32 v126, v126, v210
	v_add_f32_e32 v127, v127, v211
	global_load_dwordx4 v[208:211], v244, s[92:93]
	s_add_u32 s92, s92, 0x2000
	s_addc_u32 s93, s93, 0
	s_waitcnt vmcnt(15)
	v_add_f32_e32 v0, v0, v128
	v_add_f32_e32 v1, v1, v129
	v_add_f32_e32 v2, v2, v130
	v_add_f32_e32 v3, v3, v131
	global_load_dwordx4 v[128:131], v244, s[92:93]
	s_add_u32 s92, s92, 0x2000
	s_addc_u32 s93, s93, 0
	s_waitcnt vmcnt(15)
	v_add_f32_e32 v4, v4, v132
	v_add_f32_e32 v5, v5, v133
	v_add_f32_e32 v6, v6, v134
	v_add_f32_e32 v7, v7, v135
	global_load_dwordx4 v[132:135], v244, s[92:93]
	s_add_u32 s92, s92, 0x2000
	s_addc_u32 s93, s93, 0
	s_waitcnt vmcnt(15)
	v_add_f32_e32 v8, v8, v136
	v_add_f32_e32 v9, v9, v137
	v_add_f32_e32 v10, v10, v138
	v_add_f32_e32 v11, v11, v139
	global_load_dwordx4 v[136:139], v244, s[92:93]
	s_add_u32 s92, s92, 0x2000
	s_addc_u32 s93, s93, 0
	s_waitcnt vmcnt(15)
	v_add_f32_e32 v12, v12, v140
	v_add_f32_e32 v13, v13, v141
	v_add_f32_e32 v14, v14, v142
	v_add_f32_e32 v15, v15, v143
	global_load_dwordx4 v[140:143], v244, s[92:93]
	s_add_u32 s92, s92, 0x2000
	s_addc_u32 s93, s93, 0
	s_waitcnt vmcnt(15)
	v_add_f32_e32 v16, v16, v144
	v_add_f32_e32 v17, v17, v145
	v_add_f32_e32 v18, v18, v146
	v_add_f32_e32 v19, v19, v147
	global_load_dwordx4 v[144:147], v244, s[92:93]
	s_add_u32 s92, s92, 0x2000
	s_addc_u32 s93, s93, 0
	s_waitcnt vmcnt(15)
	v_add_f32_e32 v20, v20, v148
	v_add_f32_e32 v21, v21, v149
	v_add_f32_e32 v22, v22, v150
	v_add_f32_e32 v23, v23, v151
	global_load_dwordx4 v[148:151], v244, s[92:93]
	s_add_u32 s92, s92, 0x2000
	s_addc_u32 s93, s93, 0
	s_waitcnt vmcnt(15)
	v_add_f32_e32 v24, v24, v152
	v_add_f32_e32 v25, v25, v153
	v_add_f32_e32 v26, v26, v154
	v_add_f32_e32 v27, v27, v155
	global_load_dwordx4 v[152:155], v244, s[92:93]
	s_add_u32 s92, s92, 0x2000
	s_addc_u32 s93, s93, 0
	s_waitcnt vmcnt(15)
	v_add_f32_e32 v28, v28, v156
	v_add_f32_e32 v29, v29, v157
	v_add_f32_e32 v30, v30, v158
	v_add_f32_e32 v31, v31, v159
	global_load_dwordx4 v[156:159], v244, s[92:93]
	s_add_u32 s92, s92, 0x2000
	s_addc_u32 s93, s93, 0
	s_waitcnt vmcnt(15)
	v_add_f32_e32 v32, v32, v164
	v_add_f32_e32 v33, v33, v165
	v_add_f32_e32 v34, v34, v166
	v_add_f32_e32 v35, v35, v167
	global_load_dwordx4 v[164:167], v244, s[92:93]
	s_add_u32 s92, s92, 0x2000
	s_addc_u32 s93, s93, 0
	s_waitcnt vmcnt(15)
	v_add_f32_e32 v36, v36, v168
	v_add_f32_e32 v37, v37, v169
	v_add_f32_e32 v38, v38, v170
	v_add_f32_e32 v39, v39, v171
	global_load_dwordx4 v[168:171], v244, s[92:93]
	s_add_u32 s92, s92, 0x2000
	s_addc_u32 s93, s93, 0
	s_waitcnt vmcnt(15)
	v_add_f32_e32 v40, v40, v172
	v_add_f32_e32 v41, v41, v173
	v_add_f32_e32 v42, v42, v174
	v_add_f32_e32 v43, v43, v175
	global_load_dwordx4 v[172:175], v244, s[92:93]
	s_add_u32 s92, s92, 0x2000
	s_addc_u32 s93, s93, 0
	s_waitcnt vmcnt(15)
	v_add_f32_e32 v44, v44, v176
	v_add_f32_e32 v45, v45, v177
	v_add_f32_e32 v46, v46, v178
	v_add_f32_e32 v47, v47, v179
	global_load_dwordx4 v[176:179], v244, s[92:93]
	s_add_u32 s92, s92, 0x2000
	s_addc_u32 s93, s93, 0
	s_waitcnt vmcnt(15)
	v_add_f32_e32 v48, v48, v180
	v_add_f32_e32 v49, v49, v181
	v_add_f32_e32 v50, v50, v182
	v_add_f32_e32 v51, v51, v183
	global_load_dwordx4 v[180:183], v244, s[92:93]
	s_add_u32 s92, s92, 0x2000
	s_addc_u32 s93, s93, 0
	s_waitcnt vmcnt(15)
	v_add_f32_e32 v52, v52, v184
	v_add_f32_e32 v53, v53, v185
	v_add_f32_e32 v54, v54, v186
	v_add_f32_e32 v55, v55, v187
	global_load_dwordx4 v[184:187], v244, s[92:93]
	s_add_u32 s92, s92, 0x2000
	s_addc_u32 s93, s93, 0
	s_waitcnt vmcnt(15)
	v_add_f32_e32 v56, v56, v188
	v_add_f32_e32 v57, v57, v189
	v_add_f32_e32 v58, v58, v190
	v_add_f32_e32 v59, v59, v191
	global_load_dwordx4 v[188:191], v244, s[92:93]
	s_add_u32 s92, s92, 0x2000
	s_addc_u32 s93, s93, 0
	s_waitcnt vmcnt(15)
	v_add_f32_e32 v60, v60, v208
	v_add_f32_e32 v61, v61, v209
	v_add_f32_e32 v62, v62, v210
	v_add_f32_e32 v63, v63, v211
	global_load_dwordx4 v[208:211], v244, s[92:93]
	s_add_u32 s92, s92, 0x2000
	s_addc_u32 s93, s93, 0
	s_add_u32 s92, s92, 0xc0000
	s_addc_u32 s93, s93, 0
	s_waitcnt vmcnt(15)
	v_add_f32_e32 v64, v64, v128
	v_add_f32_e32 v65, v65, v129
	v_add_f32_e32 v66, v66, v130
	v_add_f32_e32 v67, v67, v131
	global_load_dwordx4 v[128:131], v244, s[92:93]
	s_add_u32 s92, s92, 0x2000
	s_addc_u32 s93, s93, 0
	s_waitcnt vmcnt(15)
	v_add_f32_e32 v68, v68, v132
	v_add_f32_e32 v69, v69, v133
	v_add_f32_e32 v70, v70, v134
	v_add_f32_e32 v71, v71, v135
	global_load_dwordx4 v[132:135], v244, s[92:93]
	s_add_u32 s92, s92, 0x2000
	s_addc_u32 s93, s93, 0
	s_waitcnt vmcnt(15)
	v_add_f32_e32 v72, v72, v136
	v_add_f32_e32 v73, v73, v137
	v_add_f32_e32 v74, v74, v138
	v_add_f32_e32 v75, v75, v139
	global_load_dwordx4 v[136:139], v244, s[92:93]
	s_add_u32 s92, s92, 0x2000
	s_addc_u32 s93, s93, 0
	s_waitcnt vmcnt(15)
	v_add_f32_e32 v76, v76, v140
	v_add_f32_e32 v77, v77, v141
	v_add_f32_e32 v78, v78, v142
	v_add_f32_e32 v79, v79, v143
	global_load_dwordx4 v[140:143], v244, s[92:93]
	s_add_u32 s92, s92, 0x2000
	s_addc_u32 s93, s93, 0
	s_waitcnt vmcnt(15)
	v_add_f32_e32 v80, v80, v144
	v_add_f32_e32 v81, v81, v145
	v_add_f32_e32 v82, v82, v146
	v_add_f32_e32 v83, v83, v147
	global_load_dwordx4 v[144:147], v244, s[92:93]
	s_add_u32 s92, s92, 0x2000
	s_addc_u32 s93, s93, 0
	s_waitcnt vmcnt(15)
	v_add_f32_e32 v84, v84, v148
	v_add_f32_e32 v85, v85, v149
	v_add_f32_e32 v86, v86, v150
	v_add_f32_e32 v87, v87, v151
	global_load_dwordx4 v[148:151], v244, s[92:93]
	s_add_u32 s92, s92, 0x2000
	s_addc_u32 s93, s93, 0
	s_waitcnt vmcnt(15)
	v_add_f32_e32 v88, v88, v152
	v_add_f32_e32 v89, v89, v153
	v_add_f32_e32 v90, v90, v154
	v_add_f32_e32 v91, v91, v155
	global_load_dwordx4 v[152:155], v244, s[92:93]
	s_add_u32 s92, s92, 0x2000
	s_addc_u32 s93, s93, 0
	s_waitcnt vmcnt(15)
	v_add_f32_e32 v92, v92, v156
	v_add_f32_e32 v93, v93, v157
	v_add_f32_e32 v94, v94, v158
	v_add_f32_e32 v95, v95, v159
	global_load_dwordx4 v[156:159], v244, s[92:93]
	s_add_u32 s92, s92, 0x2000
	s_addc_u32 s93, s93, 0
	s_waitcnt vmcnt(15)
	v_add_f32_e32 v96, v96, v164
	v_add_f32_e32 v97, v97, v165
	v_add_f32_e32 v98, v98, v166
	v_add_f32_e32 v99, v99, v167
	global_load_dwordx4 v[164:167], v244, s[92:93]
	s_add_u32 s92, s92, 0x2000
	s_addc_u32 s93, s93, 0
	s_waitcnt vmcnt(15)
	v_add_f32_e32 v100, v100, v168
	v_add_f32_e32 v101, v101, v169
	v_add_f32_e32 v102, v102, v170
	v_add_f32_e32 v103, v103, v171
	global_load_dwordx4 v[168:171], v244, s[92:93]
	s_add_u32 s92, s92, 0x2000
	s_addc_u32 s93, s93, 0
	s_waitcnt vmcnt(15)
	v_add_f32_e32 v104, v104, v172
	v_add_f32_e32 v105, v105, v173
	v_add_f32_e32 v106, v106, v174
	v_add_f32_e32 v107, v107, v175
	global_load_dwordx4 v[172:175], v244, s[92:93]
	s_add_u32 s92, s92, 0x2000
	s_addc_u32 s93, s93, 0
	s_waitcnt vmcnt(15)
	v_add_f32_e32 v108, v108, v176
	v_add_f32_e32 v109, v109, v177
	v_add_f32_e32 v110, v110, v178
	v_add_f32_e32 v111, v111, v179
	global_load_dwordx4 v[176:179], v244, s[92:93]
	s_add_u32 s92, s92, 0x2000
	s_addc_u32 s93, s93, 0
	s_waitcnt vmcnt(15)
	v_add_f32_e32 v112, v112, v180
	v_add_f32_e32 v113, v113, v181
	v_add_f32_e32 v114, v114, v182
	v_add_f32_e32 v115, v115, v183
	global_load_dwordx4 v[180:183], v244, s[92:93]
	s_add_u32 s92, s92, 0x2000
	s_addc_u32 s93, s93, 0
	s_waitcnt vmcnt(15)
	v_add_f32_e32 v116, v116, v184
	v_add_f32_e32 v117, v117, v185
	v_add_f32_e32 v118, v118, v186
	v_add_f32_e32 v119, v119, v187
	global_load_dwordx4 v[184:187], v244, s[92:93]
	s_add_u32 s92, s92, 0x2000
	s_addc_u32 s93, s93, 0
	s_waitcnt vmcnt(15)
	v_add_f32_e32 v120, v120, v188
	v_add_f32_e32 v121, v121, v189
	v_add_f32_e32 v122, v122, v190
	v_add_f32_e32 v123, v123, v191
	global_load_dwordx4 v[188:191], v244, s[92:93]
	s_add_u32 s92, s92, 0x2000
	s_addc_u32 s93, s93, 0
	s_waitcnt vmcnt(15)
	v_add_f32_e32 v124, v124, v208
	v_add_f32_e32 v125, v125, v209
	v_add_f32_e32 v126, v126, v210
	v_add_f32_e32 v127, v127, v211
	global_load_dwordx4 v[208:211], v244, s[92:93]
	s_add_u32 s92, s92, 0x2000
	s_addc_u32 s93, s93, 0
	s_waitcnt vmcnt(15)
	v_add_f32_e32 v0, v0, v128
	v_add_f32_e32 v1, v1, v129
	v_add_f32_e32 v2, v2, v130
	v_add_f32_e32 v3, v3, v131
	global_load_dwordx4 v[128:131], v244, s[92:93]
	s_add_u32 s92, s92, 0x2000
	s_addc_u32 s93, s93, 0
	s_waitcnt vmcnt(15)
	v_add_f32_e32 v4, v4, v132
	v_add_f32_e32 v5, v5, v133
	v_add_f32_e32 v6, v6, v134
	v_add_f32_e32 v7, v7, v135
	global_load_dwordx4 v[132:135], v244, s[92:93]
	s_add_u32 s92, s92, 0x2000
	s_addc_u32 s93, s93, 0
	s_waitcnt vmcnt(15)
	v_add_f32_e32 v8, v8, v136
	v_add_f32_e32 v9, v9, v137
	v_add_f32_e32 v10, v10, v138
	v_add_f32_e32 v11, v11, v139
	global_load_dwordx4 v[136:139], v244, s[92:93]
	s_add_u32 s92, s92, 0x2000
	s_addc_u32 s93, s93, 0
	s_waitcnt vmcnt(15)
	v_add_f32_e32 v12, v12, v140
	v_add_f32_e32 v13, v13, v141
	v_add_f32_e32 v14, v14, v142
	v_add_f32_e32 v15, v15, v143
	global_load_dwordx4 v[140:143], v244, s[92:93]
	s_add_u32 s92, s92, 0x2000
	s_addc_u32 s93, s93, 0
	s_waitcnt vmcnt(15)
	v_add_f32_e32 v16, v16, v144
	v_add_f32_e32 v17, v17, v145
	v_add_f32_e32 v18, v18, v146
	v_add_f32_e32 v19, v19, v147
	global_load_dwordx4 v[144:147], v244, s[92:93]
	s_add_u32 s92, s92, 0x2000
	s_addc_u32 s93, s93, 0
	s_waitcnt vmcnt(15)
	v_add_f32_e32 v20, v20, v148
	v_add_f32_e32 v21, v21, v149
	v_add_f32_e32 v22, v22, v150
	v_add_f32_e32 v23, v23, v151
	global_load_dwordx4 v[148:151], v244, s[92:93]
	s_add_u32 s92, s92, 0x2000
	s_addc_u32 s93, s93, 0
	s_waitcnt vmcnt(15)
	v_add_f32_e32 v24, v24, v152
	v_add_f32_e32 v25, v25, v153
	v_add_f32_e32 v26, v26, v154
	v_add_f32_e32 v27, v27, v155
	global_load_dwordx4 v[152:155], v244, s[92:93]
	s_add_u32 s92, s92, 0x2000
	s_addc_u32 s93, s93, 0
	s_waitcnt vmcnt(15)
	v_add_f32_e32 v28, v28, v156
	v_add_f32_e32 v29, v29, v157
	v_add_f32_e32 v30, v30, v158
	v_add_f32_e32 v31, v31, v159
	global_load_dwordx4 v[156:159], v244, s[92:93]
	s_add_u32 s92, s92, 0x2000
	s_addc_u32 s93, s93, 0
	s_waitcnt vmcnt(15)
	v_add_f32_e32 v32, v32, v164
	v_add_f32_e32 v33, v33, v165
	v_add_f32_e32 v34, v34, v166
	v_add_f32_e32 v35, v35, v167
	global_load_dwordx4 v[164:167], v244, s[92:93]
	s_add_u32 s92, s92, 0x2000
	s_addc_u32 s93, s93, 0
	s_waitcnt vmcnt(15)
	v_add_f32_e32 v36, v36, v168
	v_add_f32_e32 v37, v37, v169
	v_add_f32_e32 v38, v38, v170
	v_add_f32_e32 v39, v39, v171
	global_load_dwordx4 v[168:171], v244, s[92:93]
	s_add_u32 s92, s92, 0x2000
	s_addc_u32 s93, s93, 0
	s_waitcnt vmcnt(15)
	v_add_f32_e32 v40, v40, v172
	v_add_f32_e32 v41, v41, v173
	v_add_f32_e32 v42, v42, v174
	v_add_f32_e32 v43, v43, v175
	global_load_dwordx4 v[172:175], v244, s[92:93]
	s_add_u32 s92, s92, 0x2000
	s_addc_u32 s93, s93, 0
	s_waitcnt vmcnt(15)
	v_add_f32_e32 v44, v44, v176
	v_add_f32_e32 v45, v45, v177
	v_add_f32_e32 v46, v46, v178
	v_add_f32_e32 v47, v47, v179
	global_load_dwordx4 v[176:179], v244, s[92:93]
	s_add_u32 s92, s92, 0x2000
	s_addc_u32 s93, s93, 0
	s_waitcnt vmcnt(15)
	v_add_f32_e32 v48, v48, v180
	v_add_f32_e32 v49, v49, v181
	v_add_f32_e32 v50, v50, v182
	v_add_f32_e32 v51, v51, v183
	global_load_dwordx4 v[180:183], v244, s[92:93]
	s_add_u32 s92, s92, 0x2000
	s_addc_u32 s93, s93, 0
	s_waitcnt vmcnt(15)
	v_add_f32_e32 v52, v52, v184
	v_add_f32_e32 v53, v53, v185
	v_add_f32_e32 v54, v54, v186
	v_add_f32_e32 v55, v55, v187
	global_load_dwordx4 v[184:187], v244, s[92:93]
	s_add_u32 s92, s92, 0x2000
	s_addc_u32 s93, s93, 0
	s_waitcnt vmcnt(15)
	v_add_f32_e32 v56, v56, v188
	v_add_f32_e32 v57, v57, v189
	v_add_f32_e32 v58, v58, v190
	v_add_f32_e32 v59, v59, v191
	global_load_dwordx4 v[188:191], v244, s[92:93]
	s_add_u32 s92, s92, 0x2000
	s_addc_u32 s93, s93, 0
	s_waitcnt vmcnt(15)
	v_add_f32_e32 v60, v60, v208
	v_add_f32_e32 v61, v61, v209
	v_add_f32_e32 v62, v62, v210
	v_add_f32_e32 v63, v63, v211
	global_load_dwordx4 v[208:211], v244, s[92:93]
	s_add_u32 s92, s92, 0x2000
	s_addc_u32 s93, s93, 0
	s_add_u32 s92, s92, 0xc0000
	s_addc_u32 s93, s93, 0
	s_waitcnt vmcnt(15)
	v_add_f32_e32 v64, v64, v128
	v_add_f32_e32 v65, v65, v129
	v_add_f32_e32 v66, v66, v130
	v_add_f32_e32 v67, v67, v131
	s_waitcnt vmcnt(14)
	v_add_f32_e32 v68, v68, v132
	v_add_f32_e32 v69, v69, v133
	v_add_f32_e32 v70, v70, v134
	v_add_f32_e32 v71, v71, v135
	s_waitcnt vmcnt(13)
	v_add_f32_e32 v72, v72, v136
	v_add_f32_e32 v73, v73, v137
	v_add_f32_e32 v74, v74, v138
	v_add_f32_e32 v75, v75, v139
	s_waitcnt vmcnt(12)
	v_add_f32_e32 v76, v76, v140
	v_add_f32_e32 v77, v77, v141
	v_add_f32_e32 v78, v78, v142
	v_add_f32_e32 v79, v79, v143
	s_waitcnt vmcnt(11)
	v_add_f32_e32 v80, v80, v144
	v_add_f32_e32 v81, v81, v145
	v_add_f32_e32 v82, v82, v146
	v_add_f32_e32 v83, v83, v147
	s_waitcnt vmcnt(10)
	v_add_f32_e32 v84, v84, v148
	v_add_f32_e32 v85, v85, v149
	v_add_f32_e32 v86, v86, v150
	v_add_f32_e32 v87, v87, v151
	s_waitcnt vmcnt(9)
	v_add_f32_e32 v88, v88, v152
	v_add_f32_e32 v89, v89, v153
	v_add_f32_e32 v90, v90, v154
	v_add_f32_e32 v91, v91, v155
	s_waitcnt vmcnt(8)
	v_add_f32_e32 v92, v92, v156
	v_add_f32_e32 v93, v93, v157
	v_add_f32_e32 v94, v94, v158
	v_add_f32_e32 v95, v95, v159
	s_waitcnt vmcnt(7)
	v_add_f32_e32 v96, v96, v164
	v_add_f32_e32 v97, v97, v165
	v_add_f32_e32 v98, v98, v166
	v_add_f32_e32 v99, v99, v167
	s_waitcnt vmcnt(6)
	v_add_f32_e32 v100, v100, v168
	v_add_f32_e32 v101, v101, v169
	v_add_f32_e32 v102, v102, v170
	v_add_f32_e32 v103, v103, v171
	s_waitcnt vmcnt(5)
	v_add_f32_e32 v104, v104, v172
	v_add_f32_e32 v105, v105, v173
	v_add_f32_e32 v106, v106, v174
	v_add_f32_e32 v107, v107, v175
	s_waitcnt vmcnt(4)
	v_add_f32_e32 v108, v108, v176
	v_add_f32_e32 v109, v109, v177
	v_add_f32_e32 v110, v110, v178
	v_add_f32_e32 v111, v111, v179
	s_waitcnt vmcnt(3)
	v_add_f32_e32 v112, v112, v180
	v_add_f32_e32 v113, v113, v181
	v_add_f32_e32 v114, v114, v182
	v_add_f32_e32 v115, v115, v183
	s_waitcnt vmcnt(2)
	v_add_f32_e32 v116, v116, v184
	v_add_f32_e32 v117, v117, v185
	v_add_f32_e32 v118, v118, v186
	v_add_f32_e32 v119, v119, v187
	s_waitcnt vmcnt(1)
	v_add_f32_e32 v120, v120, v188
	v_add_f32_e32 v121, v121, v189
	v_add_f32_e32 v122, v122, v190
	v_add_f32_e32 v123, v123, v191
	s_waitcnt vmcnt(0)
	v_add_f32_e32 v124, v124, v208
	v_add_f32_e32 v125, v125, v209
	v_add_f32_e32 v126, v126, v210
	v_add_f32_e32 v127, v127, v211
